# grid barrier between residual-GEMM phases and the ctx-only modpass replaced by per-row-block arrival counters (sc1 stores/loads); 4 barriers fewer
# speedup vs baseline: 1.0004x; 1.0004x over previous
; #define MFMA16(a, b, c) __builtin_amdgcn_mfma_f32_16x16x32_bf16((a), (b), (c), 0, 0, 0)
; __device__ __forceinline__ void ctx_resid_gemm(const bf16_t* A  , const bf16_t* Bt  , int K, float* XC, const float* gate  , float coef, int gw, int NGW, int lane) {
;     const int fr = lane & 15, fq = lane >> 4;
;     for (int tile = gw; tile < 32 * 64; tile += NGW) {
;         const int rt = tile >> 6, ct = tile & 63;
;         const bf16_t* ap = A + (size_t)(MX + rt * 16 + fr) * K + 8 * fq; const bf16_t* bp = Bt + (size_t)(ct * 16 + fr) * K + 8 * fq;
;         f32x4 acc0 = {0.f, 0.f, 0.f, 0.f}, acc1 = acc0;
; #pragma unroll 4
;         for (int ks = 0; ks < K; ks += 64) {
;             acc0 = MFMA16(*(const bf16x8*)(ap + ks), *(const bf16x8*)(bp + ks), acc0);
;             acc1 = MFMA16(*(const bf16x8*)(ap + ks + 32), *(const bf16x8*)(bp + ks + 32), acc1);
;         }
;         const int col = ct * 16 + fr; const float gv = gate[col] * coef;
; #pragma unroll
;         for (int e = 0; e < 4; ++e) { float* xp = XC + (size_t)(rt * 16 + 4 * fq + e) * D + col; *xp = *xp + gv * (acc0[e] + acc1[e]); }
;     }
; }
.LBB0_322:
	v_lshl_add_u64 v[22:23], v[16:17], 0, v[8:9]
	v_add_co_u32_e32 v62, vcc, 0xa600000, v22
	v_lshl_add_u64 v[24:25], v[14:15], 0, v[8:9]
	s_nop 0
	v_addc_co_u32_e32 v63, vcc, 0, v23, vcc
	v_add_co_u32_e32 v64, vcc, 0xc00000, v24
	s_addk_i32 s12, 0x100
	s_nop 0
	v_addc_co_u32_e32 v65, vcc, 0, v25, vcc
	global_load_dwordx4 v[22:25], v[62:63], off
	global_load_dwordx4 v[26:29], v[62:63], off offset:64
	global_load_dwordx4 v[30:33], v[62:63], off offset:128
	global_load_dwordx4 v[34:37], v[62:63], off offset:192
	global_load_dwordx4 v[38:41], v[62:63], off offset:256
	global_load_dwordx4 v[42:45], v[62:63], off offset:320
	global_load_dwordx4 v[46:49], v[62:63], off offset:384
	global_load_dwordx4 v[50:53], v[62:63], off offset:448
	global_load_dwordx4 v[54:57], v[64:65], off
	global_load_dwordx4 v[58:61], v[64:65], off offset:64
	global_load_dwordx4 v[66:69], v[64:65], off offset:128
	global_load_dwordx4 v[70:73], v[64:65], off offset:192
	global_load_dwordx4 v[74:77], v[64:65], off offset:256
	global_load_dwordx4 v[78:81], v[64:65], off offset:320
	global_load_dwordx4 v[82:85], v[64:65], off offset:384
	global_load_dwordx4 v[86:89], v[64:65], off offset:448
	v_lshl_add_u64 v[14:15], v[14:15], 0, s[8:9]
	s_cmpk_gt_u32 s12, 0xabf
	v_lshl_add_u64 v[16:17], v[16:17], 0, s[8:9]
	s_waitcnt vmcnt(7)
	v_mfma_f32_16x16x32_bf16 v[0:3], v[22:25], v[54:57], v[0:3]
	s_waitcnt vmcnt(6)
	v_mfma_f32_16x16x32_bf16 v[4:7], v[26:29], v[58:61], v[4:7]
	s_waitcnt vmcnt(5)
	v_mfma_f32_16x16x32_bf16 v[0:3], v[30:33], v[66:69], v[0:3]
	s_waitcnt vmcnt(4)
	v_mfma_f32_16x16x32_bf16 v[4:7], v[34:37], v[70:73], v[4:7]
	s_waitcnt vmcnt(3)
	v_mfma_f32_16x16x32_bf16 v[0:3], v[38:41], v[74:77], v[0:3]
	s_waitcnt vmcnt(2)
	v_mfma_f32_16x16x32_bf16 v[4:7], v[42:45], v[78:81], v[4:7]
	s_waitcnt vmcnt(1)
	v_mfma_f32_16x16x32_bf16 v[0:3], v[46:49], v[82:85], v[0:3]
	s_waitcnt vmcnt(0)
	v_mfma_f32_16x16x32_bf16 v[4:7], v[50:53], v[86:89], v[4:7]
	s_cbranch_scc0 .LBB0_322
	v_or_b32_e32 v14, s11, v20
	v_ashrrev_i32_e32 v15, 31, v14
	v_or_b32_e32 v24, 1, v14
	v_lshlrev_b32_e32 v10, 2, v10
	v_lshlrev_b64 v[22:23], 12, v[14:15]
	v_ashrrev_i32_e32 v25, 31, v24
	v_or_b32_e32 v26, 2, v14
	v_or_b32_e32 v14, 3, v14
	v_lshl_add_u64 v[16:17], s[4:5], 0, v[10:11]
	v_lshlrev_b64 v[24:25], 12, v[24:25]
	v_ashrrev_i32_e32 v27, 31, v26
	v_ashrrev_i32_e32 v15, 31, v14
	v_lshl_add_u64 v[22:23], v[16:17], 0, v[22:23]
	global_load_dword v21, v10, s[6:7]
	global_load_dword v28, v[22:23], off
	v_lshl_add_u64 v[24:25], v[16:17], 0, v[24:25]
	v_lshlrev_b64 v[26:27], 12, v[26:27]
	v_lshlrev_b64 v[14:15], 12, v[14:15]
	v_lshl_add_u64 v[26:27], v[16:17], 0, v[26:27]
	v_lshl_add_u64 v[14:15], v[16:17], 0, v[14:15]
	global_load_dword v10, v[24:25], off
	global_load_dword v16, v[26:27], off
	global_load_dword v17, v[14:15], off
	v_add_f32_e32 v0, v0, v4
	v_add_f32_e32 v1, v1, v5
	s_add_i32 s3, s3, s28
	v_add_f32_e32 v2, v2, v6
	v_add_f32_e32 v3, v3, v7
	s_cmpk_gt_i32 s3, 0x7ff
	s_waitcnt vmcnt(4)
	v_mul_f32_e32 v4, 0.5, v21
	s_waitcnt vmcnt(3)
	v_fmac_f32_e32 v28, v0, v4
	global_store_dword v[22:23], v28, off sc1
	s_waitcnt vmcnt(3)
	v_fmac_f32_e32 v10, v1, v4
	s_waitcnt vmcnt(2)
	v_fmac_f32_e32 v16, v2, v4
	s_waitcnt vmcnt(1)
	v_fmac_f32_e32 v17, v3, v4
	global_store_dword v[24:25], v10, off sc1
	global_store_dword v[26:27], v16, off sc1
	global_store_dword v[14:15], v17, off sc1
	s_waitcnt vmcnt(0)
	s_load_dwordx2 s[100:101], s[0:1], 0xb8
	s_lshl_b32 s98, s11, 2
	v_mov_b32_e32 v100, 0
	v_mov_b32_e32 v101, 1
	s_waitcnt lgkmcnt(0)
	s_add_u32 s100, s100, 0x31d0000
	s_addc_u32 s101, s101, 0
	s_add_u32 s100, s100, s98
	s_addc_u32 s101, s101, 0
	s_mov_b64 s[98:99], exec
	s_mov_b64 exec, 1
	global_atomic_add v100, v101, s[100:101]
	s_mov_b64 exec, s[98:99]
	s_cmpk_gt_i32 s3, 0x7ff
	s_cbranch_scc0 .LBB0_321
; __device__ __forceinline__ void modpass(const float* xs_main, const float* xs_ctx, const float* mod_l, const float* g, int i, bf16_t* H, int nrows, int gw, int NGW, int lane) {
;     f32x4 gm[2][2], sh[2][2], v[2][2], vn[2][2]; int cur = -1;
;     int row = gw;
;     if (row < nrows) { const float* xr = row < MX ? xs_main + (size_t)row * D : xs_ctx + (size_t)(row - MX) * D;
; #pragma unroll
;         for (int j = 0; j < 2; ++j) { v[j][0] = *(const f32x4*)(xr + 8 * lane + 512 * j); v[j][1] = *(const f32x4*)(xr + 8 * lane + 512 * j + 4); } }
;     for (; row < nrows; row += NGW) {
;         const int nrow = row + NGW;
;         if (nrow < nrows) { const float* xr = nrow < MX ? xs_main + (size_t)nrow * D : xs_ctx + (size_t)(nrow - MX) * D;
; #pragma unroll
;             for (int j = 0; j < 2; ++j) { vn[j][0] = *(const f32x4*)(xr + 8 * lane + 512 * j); vn[j][1] = *(const f32x4*)(xr + 8 * lane + 512 * j + 4); } }
.LBB0_324:
	s_mov_b64 s[6:7], s[0:1]
	v_mov_b32_e32 v2, v206
	s_waitcnt lgkmcnt(0)
	s_barrier
	s_nop 0
	v_readfirstlane_b32 s3, v2
	s_ashr_i32 s3, s3, 6
	s_add_i32 s4, s3, s33
	s_add_i32 s4, s4, 0x8000
	s_cmp_gt_i32 s4, 0x81ff
	s_cbranch_scc1 .LBB0_383
	s_load_dwordx4 s[8:11], s[6:7], 0xb0
	s_load_dwordx2 s[14:15], s[6:7], 0x30
	v_lshlrev_b32_e32 v0, 3, v2
	v_and_b32_e32 v64, 0x1f8, v0
	v_lshlrev_b32_e32 v0, 2, v64
	s_waitcnt lgkmcnt(0)
	s_add_u32 s3, s10, 0x6300000
	s_addc_u32 s12, s11, 0
	s_add_u32 s6, s14, 0x1000
	s_addc_u32 s7, s15, 0
	s_add_i32 s13, s4, 0xffff8000
	s_ashr_i32 s5, s4, 31
	s_cmp_lt_i32 s4, 0x8000
	s_cselect_b32 s15, s5, 0
	s_cselect_b32 s14, s4, s13
	s_cselect_b32 s13, s9, s12
	s_cselect_b32 s16, s8, s3
	s_lshl_b64 s[14:15], s[14:15], 12
	s_add_u32 s14, s16, s14
	s_addc_u32 s15, s13, s15
	s_load_dwordx2 s[100:101], s[0:1], 0xb8
	s_sub_u32 s98, s4, 0x8000
	s_lshr_b32 s98, s98, 4
	s_lshl_b32 s98, s98, 6
	v_mov_b32_e32 v100, 0
	s_waitcnt lgkmcnt(0)
	s_add_u32 s100, s100, 0x31d0000
	s_addc_u32 s101, s101, 0
	s_add_u32 s100, s100, s98
	s_addc_u32 s101, s101, 0
	s_mov_b32 s98, 0
.Lcm_spin_A:
	global_load_dword v101, v100, s[100:101] sc1
	s_waitcnt vmcnt(0)
	v_readfirstlane_b32 s99, v101
	s_cmp_ge_u32 s99, 64
	s_cbranch_scc1 .Lcm_done_A
	s_sleep 1
	s_add_u32 s98, s98, 1
	s_cmp_lt_u32 s98, 0x4000
	s_cbranch_scc1 .Lcm_spin_A
.Lcm_done_A:
	global_load_dwordx4 v[12:15], v0, s[14:15] offset:16 sc1
	global_load_dwordx4 v[16:19], v0, s[14:15] sc1
	global_load_dwordx4 v[4:7], v0, s[14:15] offset:2064 sc1
	global_load_dwordx4 v[8:11], v0, s[14:15] offset:2048 sc1
	v_mbcnt_hi_u32_b32 v3, -1, v212
	v_and_b32_e32 v20, 64, v3
	v_add_u32_e32 v20, 64, v20
	v_xor_b32_e32 v21, 1, v3
	v_cmp_lt_i32_e32 vcc, v21, v20
	v_mov_b32_e32 v1, 0
	s_add_u32 s13, s10, 0x3000
	v_cndmask_b32_e32 v21, v3, v21, vcc
	v_lshlrev_b32_e32 v65, 2, v21
	v_xor_b32_e32 v21, 2, v3
	v_cmp_lt_i32_e32 vcc, v21, v20
	v_lshl_add_u64 v[66:67], s[6:7], 0, v[0:1]
	s_addc_u32 s14, s11, 0
	v_cndmask_b32_e32 v21, v3, v21, vcc
	v_lshlrev_b32_e32 v72, 2, v21
	v_xor_b32_e32 v21, 4, v3
	v_cmp_lt_i32_e32 vcc, v21, v20
	s_mov_b32 s22, -1
	v_mov_b32_e32 v78, 0x358637bd
	v_cndmask_b32_e32 v21, v3, v21, vcc
	v_lshlrev_b32_e32 v73, 2, v21
	v_xor_b32_e32 v21, 8, v3
	v_cmp_lt_i32_e32 vcc, v21, v20
	s_mov_b32 s21, 0xf800000
	v_mov_b32_e32 v79, 0x260
	v_cndmask_b32_e32 v21, v3, v21, vcc
	v_lshlrev_b32_e32 v74, 2, v21
	v_xor_b32_e32 v21, 16, v3
	v_cmp_lt_i32_e32 vcc, v21, v20
	v_mov_b32_e32 v22, v1
	v_mov_b32_e32 v23, v1
	v_cndmask_b32_e32 v21, v3, v21, vcc
	v_lshlrev_b32_e32 v75, 2, v21
	v_xor_b32_e32 v21, 32, v3
	v_cmp_lt_i32_e32 vcc, v21, v20
	v_or_b32_e32 v20, 0x200, v64
	v_lshlrev_b32_e32 v0, 2, v20
	v_lshl_add_u64 v[68:69], s[6:7], 0, v[0:1]
	s_lshl_b64 s[6:7], s[4:5], 11
	v_and_b32_e32 v0, 63, v2
	s_add_u32 s6, s10, s6
	v_cndmask_b32_e32 v3, v3, v21, vcc
	v_lshlrev_b32_e32 v0, 4, v0
	s_addc_u32 s7, s11, s7
	v_lshlrev_b32_e32 v76, 2, v3
	v_lshl_add_u64 v[2:3], s[6:7], 0, v[0:1]
	s_mov_b64 s[6:7], 0x6500400
	s_ashr_i32 s29, s28, 31
	s_add_i32 s15, s4, s28
	v_lshl_add_u64 v[70:71], v[2:3], 0, s[6:7]
	s_lshl_b64 s[6:7], s[28:29], 11
	s_ashr_i32 s20, s15, 31
	v_lshlrev_b32_e32 v77, 2, v20
	v_mov_b32_e32 v0, v1
	v_mov_b32_e32 v2, v1
	v_mov_b32_e32 v3, v1
	v_mov_b32_e32 v20, v1
	v_mov_b32_e32 v21, v1
	v_mov_b32_e32 v28, v1
	v_mov_b32_e32 v29, v1
	v_mov_b32_e32 v30, v1
	v_mov_b32_e32 v31, v1
	v_mov_b32_e32 v24, v1
	v_mov_b32_e32 v25, v1
	v_mov_b32_e32 v26, v1
	v_mov_b32_e32 v27, v1
	s_branch .LBB0_379

; #define MFMA16(a, b, c) __builtin_amdgcn_mfma_f32_16x16x32_bf16((a), (b), (c), 0, 0, 0)
; __device__ __forceinline__ void modpass(const float* xs_main, const float* xs_ctx, const float* mod_l, const float* g, int i, bf16_t* H, int nrows, int gw, int NGW, int lane) {
;     f32x4 gm[2][2], sh[2][2], v[2][2], vn[2][2]; int cur = -1;
;     int row = gw;
;     if (row < nrows) { const float* xr = row < MX ? xs_main + (size_t)row * D : xs_ctx + (size_t)(row - MX) * D;
; #pragma unroll
;         for (int j = 0; j < 2; ++j) { v[j][0] = *(const f32x4*)(xr + 8 * lane + 512 * j); v[j][1] = *(const f32x4*)(xr + 8 * lane + 512 * j + 4); } }
;     for (; row < nrows; row += NGW) {
;         const int nrow = row + NGW;
;         if (nrow < nrows) { const float* xr = nrow < MX ? xs_main + (size_t)nrow * D : xs_ctx + (size_t)(nrow - MX) * D;
; #pragma unroll
;             for (int j = 0; j < 2; ++j) { vn[j][0] = *(const f32x4*)(xr + 8 * lane + 512 * j); vn[j][1] = *(const f32x4*)(xr + 8 * lane + 512 * j + 4); } }
; __device__ __forceinline__ void ctx_resid_gemm(const bf16_t* A  , const bf16_t* Bt  , int K, float* XC, const float* gate  , float coef, int gw, int NGW, int lane) {
;     const int fr = lane & 15, fq = lane >> 4;
;     for (int tile = gw; tile < 32 * 64; tile += NGW) {
;         const int rt = tile >> 6, ct = tile & 63;
;         const bf16_t* ap = A + (size_t)(MX + rt * 16 + fr) * K + 8 * fq; const bf16_t* bp = Bt + (size_t)(ct * 16 + fr) * K + 8 * fq;
;         f32x4 acc0 = {0.f, 0.f, 0.f, 0.f}, acc1 = acc0;
; #pragma unroll 4
;         for (int ks = 0; ks < K; ks += 64) {
;             acc0 = MFMA16(*(const bf16x8*)(ap + ks), *(const bf16x8*)(bp + ks), acc0);
;             acc1 = MFMA16(*(const bf16x8*)(ap + ks + 32), *(const bf16x8*)(bp + ks + 32), acc1);
;         }
;         const int col = ct * 16 + fr; const float gv = gate[col] * coef;
; #pragma unroll
;         for (int e = 0; e < 4; ++e) { float* xp = XC + (size_t)(rt * 16 + 4 * fq + e) * D + col; *xp = *xp + gv * (acc0[e] + acc1[e]); }
;     }
; }
.LBB0_1133:
	v_lshl_add_u64 v[20:21], v[14:15], 0, v[8:9]
	v_add_co_u32_e32 v60, vcc, 0xe700000, v20
	v_lshl_add_u64 v[22:23], v[12:13], 0, v[8:9]
	s_nop 0
	v_addc_co_u32_e32 v61, vcc, 0, v21, vcc
	v_add_co_u32_e32 v62, vcc, 0x1e80000, v22
	s_addk_i32 s20, 0x100
	s_nop 0
	v_addc_co_u32_e32 v63, vcc, 0, v23, vcc
	global_load_dwordx4 v[20:23], v[60:61], off
	global_load_dwordx4 v[24:27], v[60:61], off offset:64
	global_load_dwordx4 v[28:31], v[60:61], off offset:128
	global_load_dwordx4 v[32:35], v[60:61], off offset:192
	global_load_dwordx4 v[36:39], v[60:61], off offset:256
	global_load_dwordx4 v[40:43], v[60:61], off offset:320
	global_load_dwordx4 v[44:47], v[60:61], off offset:384
	global_load_dwordx4 v[48:51], v[60:61], off offset:448
	global_load_dwordx4 v[52:55], v[62:63], off
	global_load_dwordx4 v[56:59], v[62:63], off offset:64
	global_load_dwordx4 v[66:69], v[62:63], off offset:128
	global_load_dwordx4 v[70:73], v[62:63], off offset:192
	global_load_dwordx4 v[74:77], v[62:63], off offset:256
	global_load_dwordx4 v[78:81], v[62:63], off offset:320
	global_load_dwordx4 v[82:85], v[62:63], off offset:384
	global_load_dwordx4 v[86:89], v[62:63], off offset:448
	v_lshl_add_u64 v[12:13], v[12:13], 0, s[18:19]
	s_cmpk_gt_u32 s20, 0x3bf
	v_lshl_add_u64 v[14:15], v[14:15], 0, s[18:19]
	s_waitcnt vmcnt(7)
	v_mfma_f32_16x16x32_bf16 v[0:3], v[20:23], v[52:55], v[0:3]
	s_waitcnt vmcnt(6)
	v_mfma_f32_16x16x32_bf16 v[4:7], v[24:27], v[56:59], v[4:7]
	s_waitcnt vmcnt(5)
	v_mfma_f32_16x16x32_bf16 v[0:3], v[28:31], v[66:69], v[0:3]
	s_waitcnt vmcnt(4)
	v_mfma_f32_16x16x32_bf16 v[4:7], v[32:35], v[70:73], v[4:7]
	s_waitcnt vmcnt(3)
	v_mfma_f32_16x16x32_bf16 v[0:3], v[36:39], v[74:77], v[0:3]
	s_waitcnt vmcnt(2)
	v_mfma_f32_16x16x32_bf16 v[4:7], v[40:43], v[78:81], v[4:7]
	s_waitcnt vmcnt(1)
	v_mfma_f32_16x16x32_bf16 v[0:3], v[44:47], v[82:85], v[0:3]
	s_waitcnt vmcnt(0)
	v_mfma_f32_16x16x32_bf16 v[4:7], v[48:51], v[86:89], v[4:7]
	s_cbranch_scc0 .LBB0_1133
	s_lshl_b32 s16, s6, 4
	v_or_b32_e32 v12, s9, v18
	s_and_b32 s16, s16, 0x3f0
	v_ashrrev_i32_e32 v13, 31, v12
	v_or_b32_e32 v10, s16, v16
	v_lshlrev_b64 v[20:21], 12, v[12:13]
	v_or_b32_e32 v22, 1, v12
	v_or_b32_e32 v24, 2, v12
	v_or_b32_e32 v12, 3, v12
	v_lshlrev_b32_e32 v10, 2, v10
	v_ashrrev_i32_e32 v23, 31, v22
	v_ashrrev_i32_e32 v25, 31, v24
	v_ashrrev_i32_e32 v13, 31, v12
	v_lshl_add_u64 v[14:15], s[12:13], 0, v[10:11]
	v_lshlrev_b64 v[22:23], 12, v[22:23]
	v_lshlrev_b64 v[24:25], 12, v[24:25]
	v_lshlrev_b64 v[12:13], 12, v[12:13]
	v_lshl_add_u64 v[20:21], v[14:15], 0, v[20:21]
	v_lshl_add_u64 v[22:23], v[14:15], 0, v[22:23]
	v_lshl_add_u64 v[24:25], v[14:15], 0, v[24:25]
	v_lshl_add_u64 v[12:13], v[14:15], 0, v[12:13]
	global_load_dword v14, v10, s[14:15]
	global_load_dword v15, v[20:21], off
	global_load_dword v19, v[22:23], off
	global_load_dword v26, v[24:25], off
	global_load_dword v27, v[12:13], off
	v_add_f32_e32 v0, v0, v4
	s_add_i32 s6, s6, s28
	s_add_i32 s7, s7, s8
	v_add_f32_e32 v1, v1, v5
	v_add_f32_e32 v2, v2, v6
	v_add_f32_e32 v3, v3, v7
	s_cmpk_gt_i32 s6, 0x7ff
	s_waitcnt vmcnt(3)
	v_fmac_f32_e32 v15, v0, v14
	s_waitcnt vmcnt(2)
	v_fmac_f32_e32 v19, v1, v14
	s_waitcnt vmcnt(1)
	v_fmac_f32_e32 v26, v2, v14
	s_waitcnt vmcnt(0)
	v_fmac_f32_e32 v27, v3, v14
	global_store_dword v[20:21], v15, off sc1
	global_store_dword v[22:23], v19, off sc1
	global_store_dword v[24:25], v26, off sc1
	global_store_dword v[12:13], v27, off sc1
	s_waitcnt vmcnt(0)
	s_load_dwordx2 s[100:101], s[0:1], 0xb8
	s_lshl_b32 s98, s9, 2
	v_mov_b32_e32 v100, 0
	v_mov_b32_e32 v101, 1
	s_waitcnt lgkmcnt(0)
	s_add_u32 s100, s100, 0x31d0800
	s_addc_u32 s101, s101, 0
	s_add_u32 s100, s100, s98
	s_addc_u32 s101, s101, 0
	s_mov_b64 s[98:99], exec
	s_mov_b64 exec, 1
	global_atomic_add v100, v101, s[100:101]
	s_mov_b64 exec, s[98:99]
	s_cmpk_gt_i32 s6, 0x7ff
	s_cbranch_scc0 .LBB0_1132
.LBB0_1135:
	s_mov_b64 s[18:19], s[0:1]
	v_mov_b32_e32 v2, v206
	s_waitcnt lgkmcnt(0)
	s_barrier
	s_nop 0
	v_readfirstlane_b32 s6, v2
	s_ashr_i32 s6, s6, 6
	s_add_i32 s10, s6, s33
	s_add_i32 s10, s10, 0x8000
	s_cmp_gt_i32 s10, 0x81ff
	s_cbranch_scc1 .LBB0_1194
	s_load_dwordx4 s[12:15], s[18:19], 0xb0
	s_load_dwordx2 s[8:9], s[18:19], 0x30
	v_lshlrev_b32_e32 v0, 3, v2
	v_and_b32_e32 v64, 0x1f8, v0
	v_lshlrev_b32_e32 v0, 2, v64
	s_waitcnt lgkmcnt(0)
	s_add_u32 s6, s14, 0x6300000
	s_addc_u32 s7, s15, 0
	s_add_u32 s16, s8, 0x2000
	s_addc_u32 s17, s9, 0
	s_add_i32 s8, s10, 0xffff8000
	s_ashr_i32 s11, s10, 31
	s_cmp_lt_i32 s10, 0x8000
	s_cselect_b32 s9, s11, 0
	s_cselect_b32 s8, s10, s8
	s_cselect_b32 s18, s13, s7
	s_cselect_b32 s19, s12, s6
	s_lshl_b64 s[8:9], s[8:9], 12
	s_add_u32 s8, s19, s8
	s_addc_u32 s9, s18, s9
	s_load_dwordx2 s[100:101], s[0:1], 0xb8
	s_sub_u32 s98, s10, 0x8000
	s_lshr_b32 s98, s98, 4
	s_lshl_b32 s98, s98, 6
	v_mov_b32_e32 v100, 0
	s_waitcnt lgkmcnt(0)
	s_add_u32 s100, s100, 0x31d0800
	s_addc_u32 s101, s101, 0
	s_add_u32 s100, s100, s98
	s_addc_u32 s101, s101, 0
	s_mov_b32 s98, 0

; __device__ __forceinline__ void modpass(const float* xs_main, const float* xs_ctx, const float* mod_l, const float* g, int i, bf16_t* H, int nrows, int gw, int NGW, int lane) {
;     f32x4 gm[2][2], sh[2][2], v[2][2], vn[2][2]; int cur = -1;
;     int row = gw;
;     if (row < nrows) { const float* xr = row < MX ? xs_main + (size_t)row * D : xs_ctx + (size_t)(row - MX) * D;
; #pragma unroll
;         for (int j = 0; j < 2; ++j) { v[j][0] = *(const f32x4*)(xr + 8 * lane + 512 * j); v[j][1] = *(const f32x4*)(xr + 8 * lane + 512 * j + 4); } }
;     for (; row < nrows; row += NGW) {
;         const int nrow = row + NGW;
;         if (nrow < nrows) { const float* xr = nrow < MX ? xs_main + (size_t)nrow * D : xs_ctx + (size_t)(nrow - MX) * D;
; #pragma unroll
;             for (int j = 0; j < 2; ++j) { vn[j][0] = *(const f32x4*)(xr + 8 * lane + 512 * j); vn[j][1] = *(const f32x4*)(xr + 8 * lane + 512 * j + 4); } }
.Lcm_done_C:
	global_load_dwordx4 v[12:15], v0, s[8:9] offset:16 sc1
	global_load_dwordx4 v[16:19], v0, s[8:9] sc1
	global_load_dwordx4 v[4:7], v0, s[8:9] offset:2064 sc1
	global_load_dwordx4 v[8:11], v0, s[8:9] offset:2048 sc1
	v_xor_b32_e32 v3, 1, v202
	v_cmp_lt_i32_e32 vcc, v3, v203
	v_mov_b32_e32 v1, 0
	v_or_b32_e32 v20, 0x200, v64
	v_cndmask_b32_e32 v3, v202, v3, vcc
	v_lshlrev_b32_e32 v65, 2, v3
	v_xor_b32_e32 v3, 2, v202
	v_cmp_lt_i32_e32 vcc, v3, v203
	s_add_u32 s8, s14, 0x6000
	v_lshl_add_u64 v[66:67], s[16:17], 0, v[0:1]
	v_cndmask_b32_e32 v3, v202, v3, vcc
	v_lshlrev_b32_e32 v72, 2, v3
	v_xor_b32_e32 v3, 4, v202
	v_cmp_lt_i32_e32 vcc, v3, v203
	v_lshlrev_b32_e32 v0, 2, v20
	s_addc_u32 s9, s15, 0
	v_cndmask_b32_e32 v3, v202, v3, vcc
	v_lshlrev_b32_e32 v73, 2, v3
	v_xor_b32_e32 v3, 8, v202
	v_cmp_lt_i32_e32 vcc, v3, v203
	v_lshl_add_u64 v[68:69], s[16:17], 0, v[0:1]
	s_lshl_b64 s[16:17], s[10:11], 11
	v_cndmask_b32_e32 v3, v202, v3, vcc
	v_cmp_lt_i32_e32 vcc, v204, v203
	v_lshlrev_b32_e32 v74, 2, v3
	v_and_b32_e32 v0, 63, v2
	v_cndmask_b32_e32 v3, v202, v204, vcc
	v_lshlrev_b32_e32 v75, 2, v3
	v_xor_b32_e32 v3, 32, v202
	v_cmp_lt_i32_e32 vcc, v3, v203
	s_add_u32 s14, s14, s16
	v_lshlrev_b32_e32 v0, 4, v0
	v_cndmask_b32_e32 v3, v202, v3, vcc
	s_addc_u32 s15, s15, s17
	v_lshlrev_b32_e32 v76, 2, v3
	v_lshl_add_u64 v[2:3], s[14:15], 0, v[0:1]
	s_mov_b64 s[14:15], 0x6500400
	s_ashr_i32 s29, s28, 31
	s_add_i32 s20, s10, s28
	s_mov_b32 s23, -1
	v_lshl_add_u64 v[70:71], v[2:3], 0, s[14:15]
	s_lshl_b64 s[14:15], s[28:29], 11
	s_ashr_i32 s21, s20, 31
	v_lshlrev_b32_e32 v77, 2, v20
	v_mov_b32_e32 v78, 0x358637bd
	s_mov_b32 s22, 0xf800000
	v_mov_b32_e32 v79, 0x260
	v_mov_b32_e32 v0, v1
	v_mov_b32_e32 v2, v1
	v_mov_b32_e32 v3, v1
	v_mov_b32_e32 v20, v1
	v_mov_b32_e32 v21, v1
	v_mov_b32_e32 v22, v1
	v_mov_b32_e32 v23, v1
	v_mov_b32_e32 v28, v1
	v_mov_b32_e32 v29, v1
	v_mov_b32_e32 v30, v1
	v_mov_b32_e32 v31, v1
	v_mov_b32_e32 v24, v1
	v_mov_b32_e32 v25, v1
	v_mov_b32_e32 v26, v1
	v_mov_b32_e32 v27, v1
	s_branch .LBB0_1190

; #define MFMA16(a, b, c) __builtin_amdgcn_mfma_f32_16x16x32_bf16((a), (b), (c), 0, 0, 0)
; __device__ __forceinline__ void modpass(const float* xs_main, const float* xs_ctx, const float* mod_l, const float* g, int i, bf16_t* H, int nrows, int gw, int NGW, int lane) {
;     f32x4 gm[2][2], sh[2][2], v[2][2], vn[2][2]; int cur = -1;
;     int row = gw;
;     if (row < nrows) { const float* xr = row < MX ? xs_main + (size_t)row * D : xs_ctx + (size_t)(row - MX) * D;
; #pragma unroll
;         for (int j = 0; j < 2; ++j) { v[j][0] = *(const f32x4*)(xr + 8 * lane + 512 * j); v[j][1] = *(const f32x4*)(xr + 8 * lane + 512 * j + 4); } }
;     for (; row < nrows; row += NGW) {
;         const int nrow = row + NGW;
;         if (nrow < nrows) { const float* xr = nrow < MX ? xs_main + (size_t)nrow * D : xs_ctx + (size_t)(nrow - MX) * D;
; #pragma unroll
;             for (int j = 0; j < 2; ++j) { vn[j][0] = *(const f32x4*)(xr + 8 * lane + 512 * j); vn[j][1] = *(const f32x4*)(xr + 8 * lane + 512 * j + 4); } }
; __device__ __forceinline__ void ctx_resid_gemm(const bf16_t* A  , const bf16_t* Bt  , int K, float* XC, const float* gate  , float coef, int gw, int NGW, int lane) {
;     const int fr = lane & 15, fq = lane >> 4;
;     for (int tile = gw; tile < 32 * 64; tile += NGW) {
;         const int rt = tile >> 6, ct = tile & 63;
;         const bf16_t* ap = A + (size_t)(MX + rt * 16 + fr) * K + 8 * fq; const bf16_t* bp = Bt + (size_t)(ct * 16 + fr) * K + 8 * fq;
;         f32x4 acc0 = {0.f, 0.f, 0.f, 0.f}, acc1 = acc0;
; #pragma unroll 4
;         for (int ks = 0; ks < K; ks += 64) {
;             acc0 = MFMA16(*(const bf16x8*)(ap + ks), *(const bf16x8*)(bp + ks), acc0);
;             acc1 = MFMA16(*(const bf16x8*)(ap + ks + 32), *(const bf16x8*)(bp + ks + 32), acc1);
;         }
;         const int col = ct * 16 + fr; const float gv = gate[col] * coef;
; #pragma unroll
;         for (int e = 0; e < 4; ++e) { float* xp = XC + (size_t)(rt * 16 + 4 * fq + e) * D + col; *xp = *xp + gv * (acc0[e] + acc1[e]); }
;     }
; }
.LBB0_1353:
	v_lshl_add_u64 v[22:23], v[16:17], 0, v[8:9]
	v_add_co_u32_e32 v62, vcc, 0xa600000, v22
	v_lshl_add_u64 v[24:25], v[14:15], 0, v[8:9]
	s_nop 0
	v_addc_co_u32_e32 v63, vcc, 0, v23, vcc
	v_add_co_u32_e32 v64, vcc, 0x2b80000, v24
	s_addk_i32 s9, 0x100
	s_nop 0
	v_addc_co_u32_e32 v65, vcc, 0, v25, vcc
	global_load_dwordx4 v[22:25], v[62:63], off
	global_load_dwordx4 v[26:29], v[62:63], off offset:64
	global_load_dwordx4 v[30:33], v[62:63], off offset:128
	global_load_dwordx4 v[34:37], v[62:63], off offset:192
	global_load_dwordx4 v[38:41], v[62:63], off offset:256
	global_load_dwordx4 v[42:45], v[62:63], off offset:320
	global_load_dwordx4 v[46:49], v[62:63], off offset:384
	global_load_dwordx4 v[50:53], v[62:63], off offset:448
	global_load_dwordx4 v[54:57], v[64:65], off
	global_load_dwordx4 v[58:61], v[64:65], off offset:64
	global_load_dwordx4 v[66:69], v[64:65], off offset:128
	global_load_dwordx4 v[70:73], v[64:65], off offset:192
	global_load_dwordx4 v[74:77], v[64:65], off offset:256
	global_load_dwordx4 v[78:81], v[64:65], off offset:320
	global_load_dwordx4 v[82:85], v[64:65], off offset:384
	global_load_dwordx4 v[86:89], v[64:65], off offset:448
	v_lshl_add_u64 v[14:15], v[14:15], 0, s[16:17]
	s_cmpk_gt_u32 s9, 0xabf
	v_lshl_add_u64 v[16:17], v[16:17], 0, s[16:17]
	s_waitcnt vmcnt(7)
	v_mfma_f32_16x16x32_bf16 v[0:3], v[22:25], v[54:57], v[0:3]
	s_waitcnt vmcnt(6)
	v_mfma_f32_16x16x32_bf16 v[4:7], v[26:29], v[58:61], v[4:7]
	s_waitcnt vmcnt(5)
	v_mfma_f32_16x16x32_bf16 v[0:3], v[30:33], v[66:69], v[0:3]
	s_waitcnt vmcnt(4)
	v_mfma_f32_16x16x32_bf16 v[4:7], v[34:37], v[70:73], v[4:7]
	s_waitcnt vmcnt(3)
	v_mfma_f32_16x16x32_bf16 v[0:3], v[38:41], v[74:77], v[0:3]
	s_waitcnt vmcnt(2)
	v_mfma_f32_16x16x32_bf16 v[4:7], v[42:45], v[78:81], v[4:7]
	s_waitcnt vmcnt(1)
	v_mfma_f32_16x16x32_bf16 v[0:3], v[46:49], v[82:85], v[0:3]
	s_waitcnt vmcnt(0)
	v_mfma_f32_16x16x32_bf16 v[4:7], v[50:53], v[86:89], v[4:7]
	s_cbranch_scc0 .LBB0_1353
	v_or_b32_e32 v14, s8, v20
	v_ashrrev_i32_e32 v15, 31, v14
	v_or_b32_e32 v24, 1, v14
	v_lshlrev_b32_e32 v10, 2, v10
	v_lshlrev_b64 v[22:23], 12, v[14:15]
	v_ashrrev_i32_e32 v25, 31, v24
	v_or_b32_e32 v26, 2, v14
	v_or_b32_e32 v14, 3, v14
	v_lshl_add_u64 v[16:17], s[12:13], 0, v[10:11]
	v_lshlrev_b64 v[24:25], 12, v[24:25]
	v_ashrrev_i32_e32 v27, 31, v26
	v_ashrrev_i32_e32 v15, 31, v14
	v_lshl_add_u64 v[22:23], v[16:17], 0, v[22:23]
	global_load_dword v21, v10, s[14:15]
	global_load_dword v28, v[22:23], off
	v_lshl_add_u64 v[24:25], v[16:17], 0, v[24:25]
	v_lshlrev_b64 v[26:27], 12, v[26:27]
	v_lshlrev_b64 v[14:15], 12, v[14:15]
	v_lshl_add_u64 v[26:27], v[16:17], 0, v[26:27]
	v_lshl_add_u64 v[14:15], v[16:17], 0, v[14:15]
	global_load_dword v10, v[24:25], off
	global_load_dword v16, v[26:27], off
	global_load_dword v17, v[14:15], off
	v_add_f32_e32 v0, v0, v4
	v_add_f32_e32 v1, v1, v5
	s_add_i32 s6, s6, s28
	v_add_f32_e32 v2, v2, v6
	v_add_f32_e32 v3, v3, v7
	s_cmpk_gt_i32 s6, 0x7ff
	s_waitcnt vmcnt(4)
	v_mul_f32_e32 v4, 0.5, v21
	s_waitcnt vmcnt(3)
	v_fmac_f32_e32 v28, v0, v4
	global_store_dword v[22:23], v28, off sc1
	s_waitcnt vmcnt(3)
	v_fmac_f32_e32 v10, v1, v4
	s_waitcnt vmcnt(2)
	v_fmac_f32_e32 v16, v2, v4
	s_waitcnt vmcnt(1)
	v_fmac_f32_e32 v17, v3, v4
	global_store_dword v[24:25], v10, off sc1
	global_store_dword v[26:27], v16, off sc1
	global_store_dword v[14:15], v17, off sc1
	s_waitcnt vmcnt(0)
	s_load_dwordx2 s[100:101], s[0:1], 0xb8
	s_lshl_b32 s98, s8, 2
	v_mov_b32_e32 v100, 0
	v_mov_b32_e32 v101, 1
	s_waitcnt lgkmcnt(0)
	s_add_u32 s100, s100, 0x31d1000
	s_addc_u32 s101, s101, 0
	s_add_u32 s100, s100, s98
	s_addc_u32 s101, s101, 0
	s_mov_b64 s[98:99], exec
	s_mov_b64 exec, 1
	global_atomic_add v100, v101, s[100:101]
	s_mov_b64 exec, s[98:99]
	s_cmpk_gt_i32 s6, 0x7ff
	s_cbranch_scc0 .LBB0_1352
.LBB0_1355:
	s_mov_b64 s[14:15], s[0:1]
	v_mov_b32_e32 v2, v206
	s_waitcnt lgkmcnt(0)
	s_barrier
	s_nop 0
	v_readfirstlane_b32 s6, v2
	s_ashr_i32 s6, s6, 6
	s_add_i32 s12, s6, s33
	s_add_i32 s12, s12, 0x8000
	s_cmp_gt_i32 s12, 0x81ff
	s_cbranch_scc1 .LBB0_1414
	s_load_dwordx4 s[16:19], s[14:15], 0xb0
	s_load_dwordx2 s[20:21], s[14:15], 0x30
	v_lshlrev_b32_e32 v0, 3, v2
	v_and_b32_e32 v64, 0x1f8, v0
	v_lshlrev_b32_e32 v0, 2, v64
	s_waitcnt lgkmcnt(0)
	s_add_u32 s6, s18, 0x6300000
	s_addc_u32 s7, s19, 0
	s_add_u32 s8, s18, 0x1b000
	s_addc_u32 s9, s19, 0
	s_add_u32 s14, s20, 0x3000
	s_addc_u32 s15, s21, 0
	s_add_i32 s20, s12, 0xffff8000
	s_ashr_i32 s13, s12, 31
	s_cmp_lt_i32 s12, 0x8000
	s_cselect_b32 s21, s13, 0
	s_cselect_b32 s20, s12, s20
	s_cselect_b32 s22, s17, s7
	s_cselect_b32 s23, s16, s6
	s_lshl_b64 s[20:21], s[20:21], 12
	s_add_u32 s20, s23, s20
	s_addc_u32 s21, s22, s21
	s_load_dwordx2 s[100:101], s[0:1], 0xb8
	s_sub_u32 s98, s12, 0x8000
	s_lshr_b32 s98, s98, 4
	s_lshl_b32 s98, s98, 6
	v_mov_b32_e32 v100, 0
	s_waitcnt lgkmcnt(0)
	s_add_u32 s100, s100, 0x31d1000
	s_addc_u32 s101, s101, 0
	s_add_u32 s100, s100, s98
	s_addc_u32 s101, s101, 0
	s_mov_b32 s98, 0

; __device__ __forceinline__ void modpass(const float* xs_main, const float* xs_ctx, const float* mod_l, const float* g, int i, bf16_t* H, int nrows, int gw, int NGW, int lane) {
;     f32x4 gm[2][2], sh[2][2], v[2][2], vn[2][2]; int cur = -1;
;     int row = gw;
;     if (row < nrows) { const float* xr = row < MX ? xs_main + (size_t)row * D : xs_ctx + (size_t)(row - MX) * D;
; #pragma unroll
;         for (int j = 0; j < 2; ++j) { v[j][0] = *(const f32x4*)(xr + 8 * lane + 512 * j); v[j][1] = *(const f32x4*)(xr + 8 * lane + 512 * j + 4); } }
;     for (; row < nrows; row += NGW) {
;         const int nrow = row + NGW;
;         if (nrow < nrows) { const float* xr = nrow < MX ? xs_main + (size_t)nrow * D : xs_ctx + (size_t)(nrow - MX) * D;
; #pragma unroll
;             for (int j = 0; j < 2; ++j) { vn[j][0] = *(const f32x4*)(xr + 8 * lane + 512 * j); vn[j][1] = *(const f32x4*)(xr + 8 * lane + 512 * j + 4); } }
.Lcm_done_D:
	global_load_dwordx4 v[12:15], v0, s[20:21] offset:16 sc1
	global_load_dwordx4 v[16:19], v0, s[20:21] sc1
	global_load_dwordx4 v[4:7], v0, s[20:21] offset:2064 sc1
	global_load_dwordx4 v[8:11], v0, s[20:21] offset:2048 sc1
	v_xor_b32_e32 v3, 1, v202
	v_cmp_lt_i32_e32 vcc, v3, v203
	v_mov_b32_e32 v1, 0
	v_or_b32_e32 v20, 0x200, v64
	v_cndmask_b32_e32 v3, v202, v3, vcc
	v_lshlrev_b32_e32 v65, 2, v3
	v_xor_b32_e32 v3, 2, v202
	v_cmp_lt_i32_e32 vcc, v3, v203
	v_lshl_add_u64 v[66:67], s[14:15], 0, v[0:1]
	v_lshlrev_b32_e32 v0, 2, v20
	v_cndmask_b32_e32 v3, v202, v3, vcc
	v_lshlrev_b32_e32 v72, 2, v3
	v_xor_b32_e32 v3, 4, v202
	v_cmp_lt_i32_e32 vcc, v3, v203
	v_lshl_add_u64 v[68:69], s[14:15], 0, v[0:1]
	s_lshl_b64 s[14:15], s[12:13], 11
	v_cndmask_b32_e32 v3, v202, v3, vcc
	v_lshlrev_b32_e32 v73, 2, v3
	v_xor_b32_e32 v3, 8, v202
	v_cmp_lt_i32_e32 vcc, v3, v203
	v_and_b32_e32 v0, 63, v2
	s_add_u32 s14, s18, s14
	v_cndmask_b32_e32 v3, v202, v3, vcc
	v_cmp_lt_i32_e32 vcc, v204, v203
	v_lshlrev_b32_e32 v74, 2, v3
	v_lshlrev_b32_e32 v0, 4, v0
	v_cndmask_b32_e32 v3, v202, v204, vcc
	v_lshlrev_b32_e32 v75, 2, v3
	v_xor_b32_e32 v3, 32, v202
	v_cmp_lt_i32_e32 vcc, v3, v203
	s_addc_u32 s15, s19, s15
	s_ashr_i32 s29, s28, 31
	v_cndmask_b32_e32 v3, v202, v3, vcc
	v_lshlrev_b32_e32 v76, 2, v3
	v_lshl_add_u64 v[2:3], s[14:15], 0, v[0:1]
	s_mov_b64 s[14:15], 0x6500400
	s_add_i32 s20, s12, s28
	s_mov_b32 s23, -1
	v_lshl_add_u64 v[70:71], v[2:3], 0, s[14:15]
	s_lshl_b64 s[14:15], s[28:29], 11
	s_ashr_i32 s21, s20, 31
	v_lshlrev_b32_e32 v77, 2, v20
	v_mov_b32_e32 v78, 0x358637bd
	s_mov_b32 s22, 0xf800000
	v_mov_b32_e32 v79, 0x260
	v_mov_b32_e32 v0, v1
	v_mov_b32_e32 v2, v1
	v_mov_b32_e32 v3, v1
	v_mov_b32_e32 v20, v1
	v_mov_b32_e32 v21, v1
	v_mov_b32_e32 v22, v1
	v_mov_b32_e32 v23, v1
	v_mov_b32_e32 v28, v1
	v_mov_b32_e32 v29, v1
	v_mov_b32_e32 v30, v1
	v_mov_b32_e32 v31, v1
	v_mov_b32_e32 v24, v1
	v_mov_b32_e32 v25, v1
	v_mov_b32_e32 v26, v1
	v_mov_b32_e32 v27, v1
	s_branch .LBB0_1410

; #define MFMA16(a, b, c) __builtin_amdgcn_mfma_f32_16x16x32_bf16((a), (b), (c), 0, 0, 0)
; __device__ __forceinline__ void modpass(const float* xs_main, const float* xs_ctx, const float* mod_l, const float* g, int i, bf16_t* H, int nrows, int gw, int NGW, int lane) {
;     f32x4 gm[2][2], sh[2][2], v[2][2], vn[2][2]; int cur = -1;
;     int row = gw;
;     if (row < nrows) { const float* xr = row < MX ? xs_main + (size_t)row * D : xs_ctx + (size_t)(row - MX) * D;
; #pragma unroll
;         for (int j = 0; j < 2; ++j) { v[j][0] = *(const f32x4*)(xr + 8 * lane + 512 * j); v[j][1] = *(const f32x4*)(xr + 8 * lane + 512 * j + 4); } }
;     for (; row < nrows; row += NGW) {
;         const int nrow = row + NGW;
;         if (nrow < nrows) { const float* xr = nrow < MX ? xs_main + (size_t)nrow * D : xs_ctx + (size_t)(nrow - MX) * D;
; #pragma unroll
;             for (int j = 0; j < 2; ++j) { vn[j][0] = *(const f32x4*)(xr + 8 * lane + 512 * j); vn[j][1] = *(const f32x4*)(xr + 8 * lane + 512 * j + 4); } }
; __device__ __forceinline__ void ctx_resid_gemm(const bf16_t* A  , const bf16_t* Bt  , int K, float* XC, const float* gate  , float coef, int gw, int NGW, int lane) {
;     const int fr = lane & 15, fq = lane >> 4;
;     for (int tile = gw; tile < 32 * 64; tile += NGW) {
;         const int rt = tile >> 6, ct = tile & 63;
;         const bf16_t* ap = A + (size_t)(MX + rt * 16 + fr) * K + 8 * fq; const bf16_t* bp = Bt + (size_t)(ct * 16 + fr) * K + 8 * fq;
;         f32x4 acc0 = {0.f, 0.f, 0.f, 0.f}, acc1 = acc0;
; #pragma unroll 4
;         for (int ks = 0; ks < K; ks += 64) {
;             acc0 = MFMA16(*(const bf16x8*)(ap + ks), *(const bf16x8*)(bp + ks), acc0);
;             acc1 = MFMA16(*(const bf16x8*)(ap + ks + 32), *(const bf16x8*)(bp + ks + 32), acc1);
;         }
;         const int col = ct * 16 + fr; const float gv = gate[col] * coef;
; #pragma unroll
;         for (int e = 0; e < 4; ++e) { float* xp = XC + (size_t)(rt * 16 + 4 * fq + e) * D + col; *xp = *xp + gv * (acc0[e] + acc1[e]); }
;     }
; }
.LBB0_1573:
	v_lshl_add_u64 v[22:23], v[16:17], 0, v[8:9]
	v_add_co_u32_e32 v62, vcc, 0xa600000, v22
	v_lshl_add_u64 v[24:25], v[14:15], 0, v[8:9]
	s_nop 0
	v_addc_co_u32_e32 v63, vcc, 0, v23, vcc
	v_add_co_u32_e32 v64, vcc, 0x3d00000, v24
	s_addk_i32 s9, 0x100
	s_nop 0
	v_addc_co_u32_e32 v65, vcc, 0, v25, vcc
	global_load_dwordx4 v[22:25], v[62:63], off
	global_load_dwordx4 v[26:29], v[62:63], off offset:64
	global_load_dwordx4 v[30:33], v[62:63], off offset:128
	global_load_dwordx4 v[34:37], v[62:63], off offset:192
	global_load_dwordx4 v[38:41], v[62:63], off offset:256
	global_load_dwordx4 v[42:45], v[62:63], off offset:320
	global_load_dwordx4 v[46:49], v[62:63], off offset:384
	global_load_dwordx4 v[50:53], v[62:63], off offset:448
	global_load_dwordx4 v[54:57], v[64:65], off
	global_load_dwordx4 v[58:61], v[64:65], off offset:64
	global_load_dwordx4 v[66:69], v[64:65], off offset:128
	global_load_dwordx4 v[70:73], v[64:65], off offset:192
	global_load_dwordx4 v[74:77], v[64:65], off offset:256
	global_load_dwordx4 v[78:81], v[64:65], off offset:320
	global_load_dwordx4 v[82:85], v[64:65], off offset:384
	global_load_dwordx4 v[86:89], v[64:65], off offset:448
	v_lshl_add_u64 v[14:15], v[14:15], 0, s[14:15]
	s_cmpk_gt_u32 s9, 0xabf
	v_lshl_add_u64 v[16:17], v[16:17], 0, s[14:15]
	s_waitcnt vmcnt(7)
	v_mfma_f32_16x16x32_bf16 v[0:3], v[22:25], v[54:57], v[0:3]
	s_waitcnt vmcnt(6)
	v_mfma_f32_16x16x32_bf16 v[4:7], v[26:29], v[58:61], v[4:7]
	s_waitcnt vmcnt(5)
	v_mfma_f32_16x16x32_bf16 v[0:3], v[30:33], v[66:69], v[0:3]
	s_waitcnt vmcnt(4)
	v_mfma_f32_16x16x32_bf16 v[4:7], v[34:37], v[70:73], v[4:7]
	s_waitcnt vmcnt(3)
	v_mfma_f32_16x16x32_bf16 v[0:3], v[38:41], v[74:77], v[0:3]
	s_waitcnt vmcnt(2)
	v_mfma_f32_16x16x32_bf16 v[4:7], v[42:45], v[78:81], v[4:7]
	s_waitcnt vmcnt(1)
	v_mfma_f32_16x16x32_bf16 v[0:3], v[46:49], v[82:85], v[0:3]
	s_waitcnt vmcnt(0)
	v_mfma_f32_16x16x32_bf16 v[4:7], v[50:53], v[86:89], v[4:7]
	s_cbranch_scc0 .LBB0_1573
	v_or_b32_e32 v14, s8, v20
	v_ashrrev_i32_e32 v15, 31, v14
	v_or_b32_e32 v24, 1, v14
	v_lshlrev_b32_e32 v10, 2, v10
	v_lshlrev_b64 v[22:23], 12, v[14:15]
	v_ashrrev_i32_e32 v25, 31, v24
	v_or_b32_e32 v26, 2, v14
	v_or_b32_e32 v14, 3, v14
	v_lshl_add_u64 v[16:17], s[10:11], 0, v[10:11]
	v_lshlrev_b64 v[24:25], 12, v[24:25]
	v_ashrrev_i32_e32 v27, 31, v26
	v_ashrrev_i32_e32 v15, 31, v14
	v_lshl_add_u64 v[22:23], v[16:17], 0, v[22:23]
	global_load_dword v21, v10, s[12:13]
	global_load_dword v28, v[22:23], off
	v_lshl_add_u64 v[24:25], v[16:17], 0, v[24:25]
	v_lshlrev_b64 v[26:27], 12, v[26:27]
	v_lshlrev_b64 v[14:15], 12, v[14:15]
	v_lshl_add_u64 v[26:27], v[16:17], 0, v[26:27]
	v_lshl_add_u64 v[14:15], v[16:17], 0, v[14:15]
	global_load_dword v10, v[24:25], off
	global_load_dword v16, v[26:27], off
	global_load_dword v17, v[14:15], off
	v_add_f32_e32 v0, v0, v4
	v_add_f32_e32 v1, v1, v5
	s_add_i32 s6, s6, s28
	v_add_f32_e32 v2, v2, v6
	v_add_f32_e32 v3, v3, v7
	s_cmpk_gt_i32 s6, 0x7ff
	s_waitcnt vmcnt(4)
	v_mul_f32_e32 v4, 0.5, v21
	s_waitcnt vmcnt(3)
	v_fmac_f32_e32 v28, v0, v4
	global_store_dword v[22:23], v28, off sc1
	s_waitcnt vmcnt(3)
	v_fmac_f32_e32 v10, v1, v4
	s_waitcnt vmcnt(2)
	v_fmac_f32_e32 v16, v2, v4
	s_waitcnt vmcnt(1)
	v_fmac_f32_e32 v17, v3, v4
	global_store_dword v[24:25], v10, off sc1
	global_store_dword v[26:27], v16, off sc1
	global_store_dword v[14:15], v17, off sc1
	s_waitcnt vmcnt(0)
	s_load_dwordx2 s[100:101], s[0:1], 0xb8
	s_lshl_b32 s98, s8, 2
	v_mov_b32_e32 v100, 0
	v_mov_b32_e32 v101, 1
	s_waitcnt lgkmcnt(0)
	s_add_u32 s100, s100, 0x31d1800
	s_addc_u32 s101, s101, 0
	s_add_u32 s100, s100, s98
	s_addc_u32 s101, s101, 0
	s_mov_b64 s[98:99], exec
	s_mov_b64 exec, 1
	global_atomic_add v100, v101, s[100:101]
	s_mov_b64 exec, s[98:99]
	s_cmpk_gt_i32 s6, 0x7ff
	s_cbranch_scc0 .LBB0_1572
.LBB0_1575:
	s_mov_b64 s[16:17], s[0:1]
	v_mov_b32_e32 v2, v206
	s_waitcnt lgkmcnt(0)
	s_barrier
	s_nop 0
	v_readfirstlane_b32 s6, v2
	s_ashr_i32 s6, s6, 6
	s_add_i32 s10, s6, s33
	s_add_i32 s10, s10, 0x8000
	s_cmp_gt_i32 s10, 0x81ff
	s_cbranch_scc1 .LBB0_1634
	s_load_dwordx4 s[12:15], s[16:17], 0xb0
	s_load_dwordx2 s[8:9], s[16:17], 0x30
	v_lshlrev_b32_e32 v0, 3, v2
	v_and_b32_e32 v64, 0x1f8, v0
	v_lshlrev_b32_e32 v0, 2, v64
	s_waitcnt lgkmcnt(0)
	s_add_u32 s6, s14, 0x6300000
	s_addc_u32 s7, s15, 0
	s_add_u32 s16, s8, 0x4000
	s_addc_u32 s17, s9, 0
	s_add_i32 s8, s10, 0xffff8000
	s_ashr_i32 s11, s10, 31
	s_cmp_lt_i32 s10, 0x8000
	s_cselect_b32 s9, s11, 0
	s_cselect_b32 s8, s10, s8
	s_cselect_b32 s18, s13, s7
	s_cselect_b32 s19, s12, s6
	s_lshl_b64 s[8:9], s[8:9], 12
	s_add_u32 s8, s19, s8
	s_addc_u32 s9, s18, s9
	s_load_dwordx2 s[100:101], s[0:1], 0xb8
	s_sub_u32 s98, s10, 0x8000
	s_lshr_b32 s98, s98, 4
	s_lshl_b32 s98, s98, 6
	v_mov_b32_e32 v100, 0
	s_waitcnt lgkmcnt(0)
	s_add_u32 s100, s100, 0x31d1800
	s_addc_u32 s101, s101, 0
	s_add_u32 s100, s100, s98
	s_addc_u32 s101, s101, 0
	s_mov_b32 s98, 0

; __device__ __forceinline__ void modpass(const float* xs_main, const float* xs_ctx, const float* mod_l, const float* g, int i, bf16_t* H, int nrows, int gw, int NGW, int lane) {
;     f32x4 gm[2][2], sh[2][2], v[2][2], vn[2][2]; int cur = -1;
;     int row = gw;
;     if (row < nrows) { const float* xr = row < MX ? xs_main + (size_t)row * D : xs_ctx + (size_t)(row - MX) * D;
; #pragma unroll
;         for (int j = 0; j < 2; ++j) { v[j][0] = *(const f32x4*)(xr + 8 * lane + 512 * j); v[j][1] = *(const f32x4*)(xr + 8 * lane + 512 * j + 4); } }
;     for (; row < nrows; row += NGW) {
;         const int nrow = row + NGW;
;         if (nrow < nrows) { const float* xr = nrow < MX ? xs_main + (size_t)nrow * D : xs_ctx + (size_t)(nrow - MX) * D;
; #pragma unroll
;             for (int j = 0; j < 2; ++j) { vn[j][0] = *(const f32x4*)(xr + 8 * lane + 512 * j); vn[j][1] = *(const f32x4*)(xr + 8 * lane + 512 * j + 4); } }
.Lcm_done_E:
	global_load_dwordx4 v[12:15], v0, s[8:9] offset:16 sc1
	global_load_dwordx4 v[16:19], v0, s[8:9] sc1
	global_load_dwordx4 v[4:7], v0, s[8:9] offset:2064 sc1
	global_load_dwordx4 v[8:11], v0, s[8:9] offset:2048 sc1
	v_xor_b32_e32 v3, 1, v202
	v_cmp_lt_i32_e32 vcc, v3, v203
	v_mov_b32_e32 v1, 0
	v_or_b32_e32 v20, 0x200, v64
	v_cndmask_b32_e32 v3, v202, v3, vcc
	v_lshlrev_b32_e32 v65, 2, v3
	v_xor_b32_e32 v3, 2, v202
	v_cmp_lt_i32_e32 vcc, v3, v203
	s_add_u32 s8, s14, 0x1e000
	v_lshl_add_u64 v[66:67], s[16:17], 0, v[0:1]
	v_cndmask_b32_e32 v3, v202, v3, vcc
	v_lshlrev_b32_e32 v72, 2, v3
	v_xor_b32_e32 v3, 4, v202
	v_cmp_lt_i32_e32 vcc, v3, v203
	v_lshlrev_b32_e32 v0, 2, v20
	s_addc_u32 s9, s15, 0
	v_cndmask_b32_e32 v3, v202, v3, vcc
	v_lshlrev_b32_e32 v73, 2, v3
	v_xor_b32_e32 v3, 8, v202
	v_cmp_lt_i32_e32 vcc, v3, v203
	v_lshl_add_u64 v[68:69], s[16:17], 0, v[0:1]
	s_lshl_b64 s[16:17], s[10:11], 11
	v_cndmask_b32_e32 v3, v202, v3, vcc
	v_cmp_lt_i32_e32 vcc, v204, v203
	v_lshlrev_b32_e32 v74, 2, v3
	v_and_b32_e32 v0, 63, v2
	v_cndmask_b32_e32 v3, v202, v204, vcc
	v_lshlrev_b32_e32 v75, 2, v3
	v_xor_b32_e32 v3, 32, v202
	v_cmp_lt_i32_e32 vcc, v3, v203
	s_add_u32 s14, s14, s16
	v_lshlrev_b32_e32 v0, 4, v0
	v_cndmask_b32_e32 v3, v202, v3, vcc
	s_addc_u32 s15, s15, s17
	v_lshlrev_b32_e32 v76, 2, v3
	v_lshl_add_u64 v[2:3], s[14:15], 0, v[0:1]
	s_mov_b64 s[14:15], 0x6500400
	s_ashr_i32 s29, s28, 31
	s_add_i32 s18, s10, s28
	s_mov_b32 s21, -1
	v_lshl_add_u64 v[70:71], v[2:3], 0, s[14:15]
	s_lshl_b64 s[14:15], s[28:29], 11
	s_ashr_i32 s19, s18, 31
	v_lshlrev_b32_e32 v77, 2, v20
	v_mov_b32_e32 v78, 0x358637bd
	s_mov_b32 s20, 0xf800000
	v_mov_b32_e32 v79, 0x260
	v_mov_b32_e32 v0, v1
	v_mov_b32_e32 v2, v1
	v_mov_b32_e32 v3, v1
	v_mov_b32_e32 v20, v1
	v_mov_b32_e32 v21, v1
	v_mov_b32_e32 v22, v1
	v_mov_b32_e32 v23, v1
	v_mov_b32_e32 v28, v1
	v_mov_b32_e32 v29, v1
	v_mov_b32_e32 v30, v1
	v_mov_b32_e32 v31, v1
	v_mov_b32_e32 v24, v1
	v_mov_b32_e32 v25, v1
	v_mov_b32_e32 v26, v1
	v_mov_b32_e32 v27, v1
	s_branch .LBB0_1630
